# nt on the merge pass's O-partial loads (last reader of OA/OB)
# speedup vs baseline: 1.0052x; 1.0052x over previous
.LBB0_495:
	s_nop 0
	v_lshl_add_u64 v[8:9], s[34:35], 0, v[130:131]
	v_add_co_u32_e32 v8, vcc, s11, v8
	s_addk_i32 s10, 0x2000
	s_nop 0
	v_addc_co_u32_e32 v9, vcc, 0, v9, vcc
	global_load_dwordx4 v[84:87], v[8:9], off nt
	global_load_dwordx4 v[80:83], v[8:9], off offset:256 nt
	v_lshl_add_u64 v[8:9], s[34:35], 0, v[128:129]
	v_add_co_u32_e32 v10, vcc, s12, v8
	v_lshl_add_u64 v[128:129], v[128:129], 0, s[6:7]
	s_nop 0
	v_addc_co_u32_e32 v11, vcc, 0, v9, vcc
	global_load_dword v151, v[10:11], off
	v_add_co_u32_e32 v10, vcc, s13, v8
	v_lshl_add_u64 v[130:131], v[130:131], 0, s[8:9]
	s_nop 0
	v_addc_co_u32_e32 v11, vcc, 0, v9, vcc
	v_add_co_u32_e32 v8, vcc, s16, v8
	global_load_dword v152, v[10:11], off
	s_nop 0
	v_addc_co_u32_e32 v9, vcc, 0, v9, vcc
	global_load_dword v153, v[8:9], off
	v_lshl_add_u64 v[8:9], s[34:35], 0, v[126:127]
	v_add_co_u32_e32 v10, vcc, s17, v8
	v_lshl_add_u64 v[126:127], v[126:127], 0, s[4:5]
	s_nop 0
	v_addc_co_u32_e32 v11, vcc, 0, v9, vcc
	global_load_dwordx4 v[72:75], v[10:11], off nt
	v_add_co_u32_e32 v10, vcc, s18, v8
	s_cmpk_lt_i32 s10, 0x2000
	s_nop 0
	v_addc_co_u32_e32 v11, vcc, 0, v9, vcc
	v_add_co_u32_e32 v8, vcc, s19, v8
	global_load_dwordx4 v[76:79], v[10:11], off nt
	s_nop 0
	v_addc_co_u32_e32 v9, vcc, 0, v9, vcc
	global_load_dwordx4 v[68:71], v[8:9], off nt
	v_lshl_add_u64 v[8:9], s[34:35], 0, v[116:117]
	v_add_co_u32_e32 v8, vcc, s11, v8
	v_lshl_add_u64 v[116:117], v[116:117], 0, s[8:9]
	s_nop 0
	v_addc_co_u32_e32 v9, vcc, 0, v9, vcc
	global_load_dwordx4 v[64:67], v[8:9], off nt
	global_load_dwordx4 v[60:63], v[8:9], off offset:256 nt
	v_lshl_add_u64 v[8:9], s[34:35], 0, v[114:115]
	v_add_co_u32_e32 v10, vcc, s12, v8
	v_lshl_add_u64 v[114:115], v[114:115], 0, s[6:7]
	s_nop 0
	v_addc_co_u32_e32 v11, vcc, 0, v9, vcc
	global_load_dword v148, v[10:11], off
	v_add_co_u32_e32 v10, vcc, s13, v8
	s_waitcnt vmcnt(10)
	v_lshlrev_b32_e32 v155, 16, v85
	v_addc_co_u32_e32 v11, vcc, 0, v9, vcc
	v_add_co_u32_e32 v8, vcc, s16, v8
	global_load_dword v149, v[10:11], off
	s_nop 0
	v_addc_co_u32_e32 v9, vcc, 0, v9, vcc
	global_load_dword v150, v[8:9], off
	v_lshl_add_u64 v[8:9], s[34:35], 0, v[112:113]
	v_add_co_u32_e32 v10, vcc, s17, v8
	v_lshlrev_b32_e32 v154, 16, v84
	s_nop 0
	v_addc_co_u32_e32 v11, vcc, 0, v9, vcc
	global_load_dwordx4 v[52:55], v[10:11], off nt
	v_add_co_u32_e32 v10, vcc, s18, v8
	s_waitcnt vmcnt(12)
	v_lshlrev_b32_e32 v157, 16, v81
	v_addc_co_u32_e32 v11, vcc, 0, v9, vcc
	v_add_co_u32_e32 v8, vcc, s19, v8
	v_lshlrev_b32_e32 v156, 16, v80
	s_nop 0
	v_addc_co_u32_e32 v9, vcc, 0, v9, vcc
	v_and_b32_e32 v85, 0xffff0000, v85
	v_and_b32_e32 v84, 0xffff0000, v84
	v_and_b32_e32 v81, 0xffff0000, v81
	v_and_b32_e32 v80, 0xffff0000, v80
	global_load_dwordx4 v[56:59], v[10:11], off nt
	global_load_dwordx4 v[48:51], v[8:9], off nt
	v_lshl_add_u64 v[8:9], s[34:35], 0, v[106:107]
	v_pk_fma_f32 v[154:155], v[122:123], v[156:157], v[154:155] neg_lo:[1,0,0] neg_hi:[1,0,0]
	v_pk_fma_f32 v[80:81], v[122:123], v[80:81], v[84:85] neg_lo:[1,0,0] neg_hi:[1,0,0]
	v_add_co_u32_e32 v8, vcc, s11, v8
	v_pk_mul_f32 v[84:85], v[154:155], v[154:155]
	v_pk_mul_f32 v[156:157], v[80:81], v[80:81]
	v_lshlrev_b32_e32 v159, 16, v87
	v_lshlrev_b32_e32 v158, 16, v86
	v_lshlrev_b32_e32 v161, 16, v83
	v_lshlrev_b32_e32 v160, 16, v82
	v_and_b32_e32 v87, 0xffff0000, v87
	v_and_b32_e32 v86, 0xffff0000, v86
	v_and_b32_e32 v83, 0xffff0000, v83
	v_and_b32_e32 v82, 0xffff0000, v82
	v_addc_co_u32_e32 v9, vcc, 0, v9, vcc
	v_pk_fma_f32 v[158:159], v[122:123], v[160:161], v[158:159] neg_lo:[1,0,0] neg_hi:[1,0,0]
	v_pk_fma_f32 v[82:83], v[122:123], v[82:83], v[86:87] neg_lo:[1,0,0] neg_hi:[1,0,0]
	v_add_f32_e32 v84, v84, v156
	global_load_dwordx4 v[44:47], v[8:9], off nt
	global_load_dwordx4 v[40:43], v[8:9], off offset:256 nt
	v_lshl_add_u64 v[8:9], s[34:35], 0, v[104:105]
	v_mov_b32_e32 v86, v82
	v_mov_b32_e32 v87, v158
	v_add_f32_e32 v84, v85, v84
	v_add_co_u32_e32 v10, vcc, s12, v8
	v_pk_mul_f32 v[86:87], v[86:87], v[86:87]
	v_add_f32_e32 v84, v157, v84
	v_addc_co_u32_e32 v11, vcc, 0, v9, vcc
	v_mov_b32_e32 v160, v83
	v_mov_b32_e32 v161, v159
	v_add_f32_e32 v84, v87, v84
	global_load_dword v145, v[10:11], off
	v_add_co_u32_e32 v10, vcc, s13, v8
	v_pk_mul_f32 v[160:161], v[160:161], v[160:161]
	v_add_f32_e32 v84, v86, v84
	v_addc_co_u32_e32 v11, vcc, 0, v9, vcc
	v_add_f32_e32 v84, v161, v84
	v_add_co_u32_e32 v8, vcc, s16, v8
	v_add_f32_e32 v84, v160, v84
	s_nop 0
	v_addc_co_u32_e32 v9, vcc, 0, v9, vcc
	ds_bpermute_b32 v85, v136, v84
	global_load_dword v146, v[10:11], off
	global_load_dword v147, v[8:9], off
	v_lshl_add_u64 v[8:9], s[34:35], 0, v[102:103]
	v_add_co_u32_e32 v10, vcc, s17, v8
	s_waitcnt lgkmcnt(0)
	v_add_f32_e32 v84, v84, v85
	v_addc_co_u32_e32 v11, vcc, 0, v9, vcc
	global_load_dwordx4 v[32:35], v[10:11], off nt
	v_add_co_u32_e32 v10, vcc, s18, v8
	ds_bpermute_b32 v85, v137, v84
	s_nop 0
	v_addc_co_u32_e32 v11, vcc, 0, v9, vcc
	v_add_co_u32_e32 v8, vcc, s19, v8
	global_load_dwordx4 v[36:39], v[10:11], off nt
	s_nop 0
	v_addc_co_u32_e32 v9, vcc, 0, v9, vcc
	global_load_dwordx4 v[28:31], v[8:9], off nt
	v_lshl_add_u64 v[8:9], s[34:35], 0, v[94:95]
	v_add_co_u32_e32 v8, vcc, s11, v8
	s_waitcnt lgkmcnt(0)
	v_add_f32_e32 v84, v84, v85
	v_addc_co_u32_e32 v9, vcc, 0, v9, vcc
	global_load_dwordx4 v[24:27], v[8:9], off nt
	global_load_dwordx4 v[20:23], v[8:9], off offset:256 nt
	v_lshl_add_u64 v[8:9], s[34:35], 0, v[92:93]
	v_add_co_u32_e32 v10, vcc, s12, v8
	ds_bpermute_b32 v85, v138, v84
	s_nop 0
	v_addc_co_u32_e32 v11, vcc, 0, v9, vcc
	global_load_dword v142, v[10:11], off
	v_add_co_u32_e32 v10, vcc, s13, v8
	s_waitcnt lgkmcnt(0)
	v_add_f32_e32 v84, v84, v85
	v_addc_co_u32_e32 v11, vcc, 0, v9, vcc
	v_add_co_u32_e32 v8, vcc, s16, v8
	global_load_dword v143, v[10:11], off
	s_nop 0
	v_addc_co_u32_e32 v9, vcc, 0, v9, vcc
	global_load_dword v144, v[8:9], off
	v_lshl_add_u64 v[8:9], s[34:35], 0, v[90:91]
	ds_bpermute_b32 v85, v139, v84
	v_add_co_u32_e32 v10, vcc, s17, v8
	v_lshl_add_u64 v[90:91], v[90:91], 0, s[4:5]
	s_nop 0
	v_addc_co_u32_e32 v11, vcc, 0, v9, vcc
	global_load_dwordx4 v[12:15], v[10:11], off nt
	v_add_co_u32_e32 v10, vcc, s18, v8
	s_waitcnt lgkmcnt(0)
	v_add_f32_e32 v84, v84, v85
	v_addc_co_u32_e32 v11, vcc, 0, v9, vcc
	v_add_co_u32_e32 v8, vcc, s19, v8
	v_fmamk_f32 v84, v84, 0x3c000000, v140
	s_nop 0
	v_addc_co_u32_e32 v9, vcc, 0, v9, vcc
	v_cmp_gt_f32_e32 vcc, s21, v84
	v_mul_f32_e32 v85, 0x4f800000, v84
	global_load_dwordx4 v[16:19], v[10:11], off nt
	v_cndmask_b32_e32 v84, v84, v85, vcc
	v_sqrt_f32_e32 v85, v84
	global_load_dwordx4 v[8:11], v[8:9], off nt
	v_lshl_add_u64 v[92:93], v[92:93], 0, s[6:7]
	v_lshl_add_u64 v[94:95], v[94:95], 0, s[8:9]
	v_add_u32_e32 v86, -1, v85
	v_fma_f32 v87, -v86, v85, v84
	v_cmp_ge_f32_e64 s[0:1], 0, v87
	v_add_u32_e32 v87, 1, v85
	v_lshl_add_u64 v[102:103], v[102:103], 0, s[4:5]
	v_cndmask_b32_e64 v86, v85, v86, s[0:1]
	v_fma_f32 v85, -v87, v85, v84
	v_cmp_lt_f32_e64 s[0:1], 0, v85
	v_lshl_add_u64 v[104:105], v[104:105], 0, s[6:7]
	v_lshl_add_u64 v[106:107], v[106:107], 0, s[8:9]
	v_cndmask_b32_e64 v85, v86, v87, s[0:1]
	v_mul_f32_e32 v86, 0x37800000, v85
	v_cndmask_b32_e32 v85, v85, v86, vcc
	v_cmp_class_f32_e32 vcc, v84, v141
	v_lshl_add_u64 v[112:113], v[112:113], 0, s[4:5]
	s_nop 0
	v_cndmask_b32_e32 v84, v85, v84, vcc
	v_div_scale_f32 v85, s[0:1], v84, v84, s22
	v_rcp_f32_e32 v86, v85
	s_nop 0
	v_fma_f32 v87, -v85, v86, 1.0
	v_fmac_f32_e32 v86, v87, v86
	v_div_scale_f32 v87, vcc, s22, v84, s22
	v_mul_f32_e32 v156, v87, v86
	v_fma_f32 v157, -v85, v156, v87
	v_fmac_f32_e32 v156, v157, v86
	v_fma_f32 v85, -v85, v156, v87
	v_div_fmas_f32 v85, v85, v86, v156
	v_div_fixup_f32 v84, v85, v84, s22
	v_pk_mul_f32 v[82:83], v[82:83], v[84:85] op_sel_hi:[1,0]
	v_pk_mul_f32 v[86:87], v[154:155], v[84:85] op_sel_hi:[1,0]
	v_pk_mul_f32 v[82:83], v[4:5], v[82:83]
	v_pk_mul_f32 v[86:87], v[2:3], v[86:87]
	v_pk_mul_f32 v[80:81], v[80:81], v[84:85] op_sel_hi:[1,0]
	v_pk_mul_f32 v[154:155], v[158:159], v[84:85] op_sel_hi:[1,0]
	v_bfe_u32 v84, v83, 16, 1
	v_bfe_u32 v85, v82, 16, 1
	v_pk_mul_f32 v[80:81], v[124:125], v[80:81]
	v_add3_u32 v82, v82, v85, s23
	v_add3_u32 v83, v83, v84, s23
	v_cvt_pk_bf16_f32 v80, v86, v80
	v_cvt_pk_bf16_f32 v81, v87, v81
	v_pk_mul_f32 v[154:155], v[6:7], v[154:155]
	v_bfe_u32 v156, v154, 16, 1
	v_bfe_u32 v157, v155, 16, 1
	v_add3_u32 v155, v155, v157, s23
	v_add3_u32 v154, v154, v156, s23
	v_lshl_add_u64 v[84:85], v[100:101], 0, v[134:135]
	v_lshrrev_b32_e32 v86, 16, v154
	v_lshrrev_b32_e32 v87, 16, v155
	v_add_co_u32_e32 v84, vcc, s24, v84
	v_and_or_b32 v83, v83, s20, v87
	v_and_or_b32 v82, v82, s20, v86
	v_addc_co_u32_e32 v85, vcc, -1, v85, vcc
	global_store_dwordx4 v[84:85], v[80:83], off offset:-256 sc1
	v_lshl_add_u64 v[134:135], v[134:135], 0, s[8:9]
	s_waitcnt vmcnt(28)
	v_max3_f32 v80, v151, v152, v153
	v_sub_f32_e32 v81, v151, v80
	v_exp_f32_e32 v83, v81
	v_sub_f32_e32 v81, v152, v80
	v_exp_f32_e32 v82, v81
	v_sub_f32_e32 v80, v153, v80
	v_exp_f32_e32 v80, v80
	v_add_f32_e32 v81, v83, v82
	v_add_f32_e32 v81, v80, v81
	v_div_scale_f32 v84, s[0:1], v81, v81, 1.0
	v_rcp_f32_e32 v85, v84
	s_nop 0
	v_fma_f32 v86, -v84, v85, 1.0
	v_fmac_f32_e32 v85, v86, v85
	v_div_scale_f32 v86, vcc, 1.0, v81, 1.0
	v_mul_f32_e32 v87, v86, v85
	v_fma_f32 v151, -v84, v87, v86
	v_fmac_f32_e32 v87, v151, v85
	v_fma_f32 v84, -v84, v87, v86
	v_div_fmas_f32 v84, v84, v85, v87
	v_div_fixup_f32 v84, v84, v81, 1.0
	v_pk_mul_f32 v[82:83], v[82:83], v[84:85] op_sel_hi:[1,0]
	s_waitcnt vmcnt(26)
	v_lshlrev_b32_e32 v87, 16, v77
	v_lshlrev_b32_e32 v86, 16, v72
	v_mul_f32_e32 v80, v80, v84
	v_lshlrev_b32_e32 v85, 16, v73
	v_lshlrev_b32_e32 v84, 16, v76
	v_pk_mul_f32 v[86:87], v[82:83], v[86:87] op_sel:[1,0] op_sel_hi:[0,1]
	v_pk_fma_f32 v[84:85], v[82:83], v[84:85], v[86:87]
	s_waitcnt vmcnt(25)
	v_lshlrev_b32_e32 v87, 16, v69
	v_lshlrev_b32_e32 v86, 16, v68
	v_pk_fma_f32 v[84:85], v[80:81], v[86:87], v[84:85] op_sel_hi:[0,1,1]
	v_and_b32_e32 v87, 0xffff0000, v73
	v_and_b32_e32 v73, 0xffff0000, v77
	v_and_b32_e32 v72, 0xffff0000, v72
	v_and_b32_e32 v86, 0xffff0000, v76
	v_pk_mul_f32 v[72:73], v[82:83], v[72:73] op_sel:[1,0] op_sel_hi:[0,1]
	v_pk_fma_f32 v[72:73], v[82:83], v[86:87], v[72:73]
	v_and_b32_e32 v69, 0xffff0000, v69
	v_and_b32_e32 v68, 0xffff0000, v68
	v_lshlrev_b32_e32 v77, 16, v79
	v_lshlrev_b32_e32 v76, 16, v74
	v_pk_fma_f32 v[68:69], v[80:81], v[68:69], v[72:73] op_sel_hi:[0,1,1]
	v_lshlrev_b32_e32 v73, 16, v75
	v_lshlrev_b32_e32 v72, 16, v78
	v_pk_mul_f32 v[76:77], v[82:83], v[76:77] op_sel:[1,0] op_sel_hi:[0,1]
	v_pk_fma_f32 v[72:73], v[82:83], v[72:73], v[76:77]
	v_lshlrev_b32_e32 v77, 16, v71
	v_lshlrev_b32_e32 v76, 16, v70
	v_pk_fma_f32 v[72:73], v[80:81], v[76:77], v[72:73] op_sel_hi:[0,1,1]
	v_and_b32_e32 v77, 0xffff0000, v75
	v_and_b32_e32 v75, 0xffff0000, v79
	v_and_b32_e32 v74, 0xffff0000, v74
	v_and_b32_e32 v76, 0xffff0000, v78
	v_pk_mul_f32 v[74:75], v[82:83], v[74:75] op_sel:[1,0] op_sel_hi:[0,1]
	v_pk_fma_f32 v[74:75], v[82:83], v[76:77], v[74:75]
	v_and_b32_e32 v71, 0xffff0000, v71
	v_and_b32_e32 v70, 0xffff0000, v70
	v_cvt_pk_bf16_f32 v69, v85, v69
	v_cvt_pk_bf16_f32 v68, v84, v68
	v_pk_fma_f32 v[70:71], v[80:81], v[70:71], v[74:75] op_sel_hi:[0,1,1]
	v_cvt_pk_bf16_f32 v70, v72, v70
	v_cvt_pk_bf16_f32 v71, v73, v71
	v_lshl_add_u64 v[72:73], v[88:89], 0, v[132:133]
	v_add_co_u32_e32 v72, vcc, s25, v72
	v_addc_co_u32_e32 v73, vcc, -1, v73, vcc
	global_store_dwordx4 v[72:73], v[68:71], off offset:-3072 sc1
	s_waitcnt vmcnt(25)
	v_lshlrev_b32_e32 v73, 16, v67
	v_lshlrev_b32_e32 v72, 16, v66
	v_lshlrev_b32_e32 v69, 16, v65
	v_lshlrev_b32_e32 v68, 16, v64
	s_waitcnt vmcnt(24)
	v_lshlrev_b32_e32 v71, 16, v61
	v_lshlrev_b32_e32 v70, 16, v60
	v_and_b32_e32 v65, 0xffff0000, v65
	v_and_b32_e32 v64, 0xffff0000, v64
	v_and_b32_e32 v61, 0xffff0000, v61
	v_and_b32_e32 v60, 0xffff0000, v60
	v_pk_fma_f32 v[68:69], v[122:123], v[70:71], v[68:69] neg_lo:[1,0,0] neg_hi:[1,0,0]
	v_pk_fma_f32 v[60:61], v[122:123], v[60:61], v[64:65] neg_lo:[1,0,0] neg_hi:[1,0,0]
	v_pk_mul_f32 v[64:65], v[68:69], v[68:69]
	v_pk_mul_f32 v[70:71], v[60:61], v[60:61]
	v_lshlrev_b32_e32 v75, 16, v63
	v_lshlrev_b32_e32 v74, 16, v62
	v_and_b32_e32 v67, 0xffff0000, v67
	v_and_b32_e32 v66, 0xffff0000, v66
	v_and_b32_e32 v63, 0xffff0000, v63
	v_and_b32_e32 v62, 0xffff0000, v62
	v_pk_fma_f32 v[72:73], v[122:123], v[74:75], v[72:73] neg_lo:[1,0,0] neg_hi:[1,0,0]
	v_pk_fma_f32 v[62:63], v[122:123], v[62:63], v[66:67] neg_lo:[1,0,0] neg_hi:[1,0,0]
	v_add_f32_e32 v64, v64, v70
	v_mov_b32_e32 v66, v62
	v_mov_b32_e32 v67, v72
	v_add_f32_e32 v64, v65, v64
	v_pk_mul_f32 v[66:67], v[66:67], v[66:67]
	v_add_f32_e32 v64, v71, v64
	v_mov_b32_e32 v74, v63
	v_mov_b32_e32 v75, v73
	v_add_f32_e32 v64, v67, v64
	v_pk_mul_f32 v[74:75], v[74:75], v[74:75]
	v_add_f32_e32 v64, v66, v64
	v_add_f32_e32 v64, v75, v64
	v_add_f32_e32 v64, v74, v64
	ds_bpermute_b32 v65, v136, v64
	v_lshl_add_u64 v[132:133], v[132:133], 0, s[8:9]
	s_waitcnt lgkmcnt(0)
	v_add_f32_e32 v64, v64, v65
	ds_bpermute_b32 v65, v137, v64
	s_waitcnt lgkmcnt(0)
	v_add_f32_e32 v64, v64, v65
	ds_bpermute_b32 v65, v138, v64
	s_waitcnt lgkmcnt(0)
	v_add_f32_e32 v64, v64, v65
	ds_bpermute_b32 v65, v139, v64
	s_waitcnt lgkmcnt(0)
	v_add_f32_e32 v64, v64, v65
	v_fmamk_f32 v64, v64, 0x3c000000, v140
	v_cmp_gt_f32_e32 vcc, s21, v64
	v_mul_f32_e32 v65, 0x4f800000, v64
	s_nop 0
	v_cndmask_b32_e32 v64, v64, v65, vcc
	v_sqrt_f32_e32 v65, v64
	s_nop 0
	v_add_u32_e32 v66, -1, v65
	v_fma_f32 v67, -v66, v65, v64
	v_cmp_ge_f32_e64 s[0:1], 0, v67
	v_add_u32_e32 v67, 1, v65
	s_nop 0
	v_cndmask_b32_e64 v66, v65, v66, s[0:1]
	v_fma_f32 v65, -v67, v65, v64
	v_cmp_lt_f32_e64 s[0:1], 0, v65
	s_nop 1
	v_cndmask_b32_e64 v65, v66, v67, s[0:1]
	v_mul_f32_e32 v66, 0x37800000, v65
	v_cndmask_b32_e32 v65, v65, v66, vcc
	v_cmp_class_f32_e32 vcc, v64, v141
	s_nop 1
	v_cndmask_b32_e32 v64, v65, v64, vcc
	v_div_scale_f32 v65, s[0:1], v64, v64, s22
	v_rcp_f32_e32 v66, v65
	s_nop 0
	v_fma_f32 v67, -v65, v66, 1.0
	v_fmac_f32_e32 v66, v67, v66
	v_div_scale_f32 v67, vcc, s22, v64, s22
	v_mul_f32_e32 v70, v67, v66
	v_fma_f32 v71, -v65, v70, v67
	v_fmac_f32_e32 v70, v71, v66
	v_fma_f32 v65, -v65, v70, v67
	v_div_fmas_f32 v65, v65, v66, v70
	v_div_fixup_f32 v64, v65, v64, s22
	v_pk_mul_f32 v[62:63], v[62:63], v[64:65] op_sel_hi:[1,0]
	v_pk_mul_f32 v[66:67], v[68:69], v[64:65] op_sel_hi:[1,0]
	v_pk_mul_f32 v[62:63], v[4:5], v[62:63]
	v_pk_mul_f32 v[66:67], v[2:3], v[66:67]
	v_pk_mul_f32 v[60:61], v[60:61], v[64:65] op_sel_hi:[1,0]
	v_pk_mul_f32 v[68:69], v[72:73], v[64:65] op_sel_hi:[1,0]
	v_bfe_u32 v64, v63, 16, 1
	v_bfe_u32 v65, v62, 16, 1
	v_pk_mul_f32 v[60:61], v[124:125], v[60:61]
	v_add3_u32 v62, v62, v65, s23
	v_add3_u32 v63, v63, v64, s23
	v_cvt_pk_bf16_f32 v60, v66, v60
	v_cvt_pk_bf16_f32 v61, v67, v61
	v_pk_mul_f32 v[68:69], v[6:7], v[68:69]
	v_bfe_u32 v70, v68, 16, 1
	v_bfe_u32 v71, v69, 16, 1
	v_add3_u32 v69, v69, v71, s23
	v_add3_u32 v68, v68, v70, s23
	v_lshl_add_u64 v[64:65], v[100:101], 0, v[120:121]
	v_lshrrev_b32_e32 v66, 16, v68
	v_lshrrev_b32_e32 v67, 16, v69
	v_add_co_u32_e32 v64, vcc, s24, v64
	v_and_or_b32 v63, v63, s20, v67
	v_and_or_b32 v62, v62, s20, v66
	v_addc_co_u32_e32 v65, vcc, -1, v65, vcc
	global_store_dwordx4 v[64:65], v[60:63], off offset:-256 sc1
	v_lshl_add_u64 v[120:121], v[120:121], 0, s[8:9]
	s_waitcnt vmcnt(22)
	v_max3_f32 v60, v148, v149, v150
	v_sub_f32_e32 v61, v148, v60
	v_exp_f32_e32 v63, v61
	v_sub_f32_e32 v61, v149, v60
	v_exp_f32_e32 v62, v61
	v_sub_f32_e32 v60, v150, v60
	v_exp_f32_e32 v60, v60
	v_add_f32_e32 v61, v63, v62
	v_add_f32_e32 v61, v60, v61
	v_div_scale_f32 v64, s[0:1], v61, v61, 1.0
	v_rcp_f32_e32 v65, v64
	s_nop 0
	v_fma_f32 v66, -v64, v65, 1.0
	v_fmac_f32_e32 v65, v66, v65
	v_div_scale_f32 v66, vcc, 1.0, v61, 1.0
	v_mul_f32_e32 v67, v66, v65
	v_fma_f32 v68, -v64, v67, v66
	v_fmac_f32_e32 v67, v68, v65
	v_fma_f32 v64, -v64, v67, v66
	v_div_fmas_f32 v64, v64, v65, v67
	v_div_fixup_f32 v64, v64, v61, 1.0
	v_pk_mul_f32 v[62:63], v[62:63], v[64:65] op_sel_hi:[1,0]
	s_waitcnt vmcnt(20)
	v_lshlrev_b32_e32 v67, 16, v57
	v_lshlrev_b32_e32 v66, 16, v52
	v_mul_f32_e32 v60, v60, v64
	v_lshlrev_b32_e32 v65, 16, v53
	v_lshlrev_b32_e32 v64, 16, v56
	v_pk_mul_f32 v[66:67], v[62:63], v[66:67] op_sel:[1,0] op_sel_hi:[0,1]
	v_pk_fma_f32 v[64:65], v[62:63], v[64:65], v[66:67]
	s_waitcnt vmcnt(19)
	v_lshlrev_b32_e32 v67, 16, v49
	v_lshlrev_b32_e32 v66, 16, v48
	v_pk_fma_f32 v[64:65], v[60:61], v[66:67], v[64:65] op_sel_hi:[0,1,1]
	v_and_b32_e32 v67, 0xffff0000, v53
	v_and_b32_e32 v53, 0xffff0000, v57
	v_and_b32_e32 v52, 0xffff0000, v52
	v_and_b32_e32 v66, 0xffff0000, v56
	v_pk_mul_f32 v[52:53], v[62:63], v[52:53] op_sel:[1,0] op_sel_hi:[0,1]
	v_pk_fma_f32 v[52:53], v[62:63], v[66:67], v[52:53]
	v_and_b32_e32 v49, 0xffff0000, v49
	v_and_b32_e32 v48, 0xffff0000, v48
	v_lshlrev_b32_e32 v57, 16, v59
	v_lshlrev_b32_e32 v56, 16, v54
	v_pk_fma_f32 v[48:49], v[60:61], v[48:49], v[52:53] op_sel_hi:[0,1,1]
	v_lshlrev_b32_e32 v53, 16, v55
	v_lshlrev_b32_e32 v52, 16, v58
	v_pk_mul_f32 v[56:57], v[62:63], v[56:57] op_sel:[1,0] op_sel_hi:[0,1]
	v_pk_fma_f32 v[52:53], v[62:63], v[52:53], v[56:57]
	v_lshlrev_b32_e32 v57, 16, v51
	v_lshlrev_b32_e32 v56, 16, v50
	v_pk_fma_f32 v[52:53], v[60:61], v[56:57], v[52:53] op_sel_hi:[0,1,1]
	v_and_b32_e32 v57, 0xffff0000, v55
	v_and_b32_e32 v55, 0xffff0000, v59
	v_and_b32_e32 v54, 0xffff0000, v54
	v_and_b32_e32 v56, 0xffff0000, v58
	v_pk_mul_f32 v[54:55], v[62:63], v[54:55] op_sel:[1,0] op_sel_hi:[0,1]
	v_pk_fma_f32 v[54:55], v[62:63], v[56:57], v[54:55]
	v_and_b32_e32 v51, 0xffff0000, v51
	v_and_b32_e32 v50, 0xffff0000, v50
	v_cvt_pk_bf16_f32 v49, v65, v49
	v_cvt_pk_bf16_f32 v48, v64, v48
	v_pk_fma_f32 v[50:51], v[60:61], v[50:51], v[54:55] op_sel_hi:[0,1,1]
	v_cvt_pk_bf16_f32 v50, v52, v50
	v_cvt_pk_bf16_f32 v51, v53, v51
	v_lshl_add_u64 v[52:53], v[88:89], 0, v[118:119]
	v_add_co_u32_e32 v52, vcc, s25, v52
	v_addc_co_u32_e32 v53, vcc, -1, v53, vcc
	global_store_dwordx4 v[52:53], v[48:51], off offset:-3072 sc1
	s_waitcnt vmcnt(19)
	v_lshlrev_b32_e32 v53, 16, v47
	v_lshlrev_b32_e32 v52, 16, v46
	v_lshlrev_b32_e32 v49, 16, v45
	v_lshlrev_b32_e32 v48, 16, v44
	s_waitcnt vmcnt(18)
	v_lshlrev_b32_e32 v51, 16, v41
	v_lshlrev_b32_e32 v50, 16, v40
	v_and_b32_e32 v45, 0xffff0000, v45
	v_and_b32_e32 v44, 0xffff0000, v44
	v_and_b32_e32 v41, 0xffff0000, v41
	v_and_b32_e32 v40, 0xffff0000, v40
	v_pk_fma_f32 v[48:49], v[122:123], v[50:51], v[48:49] neg_lo:[1,0,0] neg_hi:[1,0,0]
	v_pk_fma_f32 v[40:41], v[122:123], v[40:41], v[44:45] neg_lo:[1,0,0] neg_hi:[1,0,0]
	v_pk_mul_f32 v[44:45], v[48:49], v[48:49]
	v_pk_mul_f32 v[50:51], v[40:41], v[40:41]
	v_lshlrev_b32_e32 v55, 16, v43
	v_lshlrev_b32_e32 v54, 16, v42
	v_and_b32_e32 v47, 0xffff0000, v47
	v_and_b32_e32 v46, 0xffff0000, v46
	v_and_b32_e32 v43, 0xffff0000, v43
	v_and_b32_e32 v42, 0xffff0000, v42
	v_pk_fma_f32 v[52:53], v[122:123], v[54:55], v[52:53] neg_lo:[1,0,0] neg_hi:[1,0,0]
	v_pk_fma_f32 v[42:43], v[122:123], v[42:43], v[46:47] neg_lo:[1,0,0] neg_hi:[1,0,0]
	v_add_f32_e32 v44, v44, v50
	v_mov_b32_e32 v46, v42
	v_mov_b32_e32 v47, v52
	v_add_f32_e32 v44, v45, v44
	v_pk_mul_f32 v[46:47], v[46:47], v[46:47]
	v_add_f32_e32 v44, v51, v44
	v_mov_b32_e32 v54, v43
	v_mov_b32_e32 v55, v53
	v_add_f32_e32 v44, v47, v44
	v_pk_mul_f32 v[54:55], v[54:55], v[54:55]
	v_add_f32_e32 v44, v46, v44
	v_add_f32_e32 v44, v55, v44
	v_add_f32_e32 v44, v54, v44
	ds_bpermute_b32 v45, v136, v44
	v_lshl_add_u64 v[118:119], v[118:119], 0, s[8:9]
	s_waitcnt lgkmcnt(0)
	v_add_f32_e32 v44, v44, v45
	ds_bpermute_b32 v45, v137, v44
	s_waitcnt lgkmcnt(0)
	v_add_f32_e32 v44, v44, v45
	ds_bpermute_b32 v45, v138, v44
	s_waitcnt lgkmcnt(0)
	v_add_f32_e32 v44, v44, v45
	ds_bpermute_b32 v45, v139, v44
	s_waitcnt lgkmcnt(0)
	v_add_f32_e32 v44, v44, v45
	v_fmamk_f32 v44, v44, 0x3c000000, v140
	v_cmp_gt_f32_e32 vcc, s21, v44
	v_mul_f32_e32 v45, 0x4f800000, v44
	s_nop 0
	v_cndmask_b32_e32 v44, v44, v45, vcc
	v_sqrt_f32_e32 v45, v44
	s_nop 0
	v_add_u32_e32 v46, -1, v45
	v_fma_f32 v47, -v46, v45, v44
	v_cmp_ge_f32_e64 s[0:1], 0, v47
	v_add_u32_e32 v47, 1, v45
	s_nop 0
	v_cndmask_b32_e64 v46, v45, v46, s[0:1]
	v_fma_f32 v45, -v47, v45, v44
	v_cmp_lt_f32_e64 s[0:1], 0, v45
	s_nop 1
	v_cndmask_b32_e64 v45, v46, v47, s[0:1]
	v_mul_f32_e32 v46, 0x37800000, v45
	v_cndmask_b32_e32 v45, v45, v46, vcc
	v_cmp_class_f32_e32 vcc, v44, v141
	s_nop 1
	v_cndmask_b32_e32 v44, v45, v44, vcc
	v_div_scale_f32 v45, s[0:1], v44, v44, s22
	v_rcp_f32_e32 v46, v45
	s_nop 0
	v_fma_f32 v47, -v45, v46, 1.0
	v_fmac_f32_e32 v46, v47, v46
	v_div_scale_f32 v47, vcc, s22, v44, s22
	v_mul_f32_e32 v50, v47, v46
	v_fma_f32 v51, -v45, v50, v47
	v_fmac_f32_e32 v50, v51, v46
	v_fma_f32 v45, -v45, v50, v47
	v_div_fmas_f32 v45, v45, v46, v50
	v_div_fixup_f32 v44, v45, v44, s22
	v_pk_mul_f32 v[42:43], v[42:43], v[44:45] op_sel_hi:[1,0]
	v_pk_mul_f32 v[46:47], v[48:49], v[44:45] op_sel_hi:[1,0]
	v_pk_mul_f32 v[42:43], v[4:5], v[42:43]
	v_pk_mul_f32 v[46:47], v[2:3], v[46:47]
	v_pk_mul_f32 v[40:41], v[40:41], v[44:45] op_sel_hi:[1,0]
	v_pk_mul_f32 v[48:49], v[52:53], v[44:45] op_sel_hi:[1,0]
	v_bfe_u32 v44, v43, 16, 1
	v_bfe_u32 v45, v42, 16, 1
	v_pk_mul_f32 v[40:41], v[124:125], v[40:41]
	v_add3_u32 v42, v42, v45, s23
	v_add3_u32 v43, v43, v44, s23
	v_cvt_pk_bf16_f32 v40, v46, v40
	v_cvt_pk_bf16_f32 v41, v47, v41
	v_pk_mul_f32 v[48:49], v[6:7], v[48:49]
	v_bfe_u32 v50, v48, 16, 1
	v_bfe_u32 v51, v49, 16, 1
	v_add3_u32 v49, v49, v51, s23
	v_add3_u32 v48, v48, v50, s23
	v_lshl_add_u64 v[44:45], v[100:101], 0, v[110:111]
	v_lshrrev_b32_e32 v46, 16, v48
	v_lshrrev_b32_e32 v47, 16, v49
	v_add_co_u32_e32 v44, vcc, s24, v44
	v_and_or_b32 v43, v43, s20, v47
	v_and_or_b32 v42, v42, s20, v46
	v_addc_co_u32_e32 v45, vcc, -1, v45, vcc
	global_store_dwordx4 v[44:45], v[40:43], off offset:-256 sc1
	v_lshl_add_u64 v[110:111], v[110:111], 0, s[8:9]
	s_waitcnt vmcnt(16)
	v_max3_f32 v40, v145, v146, v147
	v_sub_f32_e32 v41, v145, v40
	v_exp_f32_e32 v43, v41
	v_sub_f32_e32 v41, v146, v40
	v_exp_f32_e32 v42, v41
	v_sub_f32_e32 v40, v147, v40
	v_exp_f32_e32 v40, v40
	v_add_f32_e32 v41, v43, v42
	v_add_f32_e32 v41, v40, v41
	v_div_scale_f32 v44, s[0:1], v41, v41, 1.0
	v_rcp_f32_e32 v45, v44
	s_nop 0
	v_fma_f32 v46, -v44, v45, 1.0
	v_fmac_f32_e32 v45, v46, v45
	v_div_scale_f32 v46, vcc, 1.0, v41, 1.0
	v_mul_f32_e32 v47, v46, v45
	v_fma_f32 v48, -v44, v47, v46
	v_fmac_f32_e32 v47, v48, v45
	v_fma_f32 v44, -v44, v47, v46
	v_div_fmas_f32 v44, v44, v45, v47
	v_div_fixup_f32 v44, v44, v41, 1.0
	v_pk_mul_f32 v[42:43], v[42:43], v[44:45] op_sel_hi:[1,0]
	s_waitcnt vmcnt(14)
	v_lshlrev_b32_e32 v47, 16, v37
	v_lshlrev_b32_e32 v46, 16, v32
	v_mul_f32_e32 v40, v40, v44
	v_lshlrev_b32_e32 v45, 16, v33
	v_lshlrev_b32_e32 v44, 16, v36
	v_pk_mul_f32 v[46:47], v[42:43], v[46:47] op_sel:[1,0] op_sel_hi:[0,1]
	v_pk_fma_f32 v[44:45], v[42:43], v[44:45], v[46:47]
	s_waitcnt vmcnt(13)
	v_lshlrev_b32_e32 v47, 16, v29
	v_lshlrev_b32_e32 v46, 16, v28
	v_pk_fma_f32 v[44:45], v[40:41], v[46:47], v[44:45] op_sel_hi:[0,1,1]
	v_and_b32_e32 v47, 0xffff0000, v33
	v_and_b32_e32 v33, 0xffff0000, v37
	v_and_b32_e32 v32, 0xffff0000, v32
	v_and_b32_e32 v46, 0xffff0000, v36
	v_pk_mul_f32 v[32:33], v[42:43], v[32:33] op_sel:[1,0] op_sel_hi:[0,1]
	v_pk_fma_f32 v[32:33], v[42:43], v[46:47], v[32:33]
	v_and_b32_e32 v29, 0xffff0000, v29
	v_and_b32_e32 v28, 0xffff0000, v28
	v_lshlrev_b32_e32 v37, 16, v39
	v_lshlrev_b32_e32 v36, 16, v34
	v_pk_fma_f32 v[28:29], v[40:41], v[28:29], v[32:33] op_sel_hi:[0,1,1]
	v_lshlrev_b32_e32 v33, 16, v35
	v_lshlrev_b32_e32 v32, 16, v38
	v_pk_mul_f32 v[36:37], v[42:43], v[36:37] op_sel:[1,0] op_sel_hi:[0,1]
	v_pk_fma_f32 v[32:33], v[42:43], v[32:33], v[36:37]
	v_lshlrev_b32_e32 v37, 16, v31
	v_lshlrev_b32_e32 v36, 16, v30
	v_pk_fma_f32 v[32:33], v[40:41], v[36:37], v[32:33] op_sel_hi:[0,1,1]
	v_and_b32_e32 v37, 0xffff0000, v35
	v_and_b32_e32 v35, 0xffff0000, v39
	v_and_b32_e32 v34, 0xffff0000, v34
	v_and_b32_e32 v36, 0xffff0000, v38
	v_pk_mul_f32 v[34:35], v[42:43], v[34:35] op_sel:[1,0] op_sel_hi:[0,1]
	v_pk_fma_f32 v[34:35], v[42:43], v[36:37], v[34:35]
	v_and_b32_e32 v31, 0xffff0000, v31
	v_and_b32_e32 v30, 0xffff0000, v30
	v_cvt_pk_bf16_f32 v29, v45, v29
	v_cvt_pk_bf16_f32 v28, v44, v28
	v_pk_fma_f32 v[30:31], v[40:41], v[30:31], v[34:35] op_sel_hi:[0,1,1]
	v_cvt_pk_bf16_f32 v30, v32, v30
	v_cvt_pk_bf16_f32 v31, v33, v31
	v_lshl_add_u64 v[32:33], v[88:89], 0, v[108:109]
	v_add_co_u32_e32 v32, vcc, s25, v32
	v_addc_co_u32_e32 v33, vcc, -1, v33, vcc
	global_store_dwordx4 v[32:33], v[28:31], off offset:-3072 sc1
	s_waitcnt vmcnt(13)
	v_lshlrev_b32_e32 v33, 16, v27
	v_lshlrev_b32_e32 v32, 16, v26
	v_lshlrev_b32_e32 v29, 16, v25
	v_lshlrev_b32_e32 v28, 16, v24
	s_waitcnt vmcnt(12)
	v_lshlrev_b32_e32 v31, 16, v21
	v_lshlrev_b32_e32 v30, 16, v20
	v_and_b32_e32 v25, 0xffff0000, v25
	v_and_b32_e32 v24, 0xffff0000, v24
	v_and_b32_e32 v21, 0xffff0000, v21
	v_and_b32_e32 v20, 0xffff0000, v20
	v_pk_fma_f32 v[28:29], v[122:123], v[30:31], v[28:29] neg_lo:[1,0,0] neg_hi:[1,0,0]
	v_pk_fma_f32 v[20:21], v[122:123], v[20:21], v[24:25] neg_lo:[1,0,0] neg_hi:[1,0,0]
	v_pk_mul_f32 v[24:25], v[28:29], v[28:29]
	v_pk_mul_f32 v[30:31], v[20:21], v[20:21]
	v_lshlrev_b32_e32 v35, 16, v23
	v_lshlrev_b32_e32 v34, 16, v22
	v_and_b32_e32 v27, 0xffff0000, v27
	v_and_b32_e32 v26, 0xffff0000, v26
	v_and_b32_e32 v23, 0xffff0000, v23
	v_and_b32_e32 v22, 0xffff0000, v22
	v_pk_fma_f32 v[32:33], v[122:123], v[34:35], v[32:33] neg_lo:[1,0,0] neg_hi:[1,0,0]
	v_pk_fma_f32 v[22:23], v[122:123], v[22:23], v[26:27] neg_lo:[1,0,0] neg_hi:[1,0,0]
	v_add_f32_e32 v24, v24, v30
	v_mov_b32_e32 v26, v22
	v_mov_b32_e32 v27, v32
	v_add_f32_e32 v24, v25, v24
	v_pk_mul_f32 v[26:27], v[26:27], v[26:27]
	v_add_f32_e32 v24, v31, v24
	v_mov_b32_e32 v34, v23
	v_mov_b32_e32 v35, v33
	v_add_f32_e32 v24, v27, v24
	v_pk_mul_f32 v[34:35], v[34:35], v[34:35]
	v_add_f32_e32 v24, v26, v24
	v_add_f32_e32 v24, v35, v24
	v_add_f32_e32 v24, v34, v24
	ds_bpermute_b32 v25, v136, v24
	v_lshl_add_u64 v[108:109], v[108:109], 0, s[8:9]
	s_waitcnt lgkmcnt(0)
	v_add_f32_e32 v24, v24, v25
	ds_bpermute_b32 v25, v137, v24
	s_waitcnt lgkmcnt(0)
	v_add_f32_e32 v24, v24, v25
	ds_bpermute_b32 v25, v138, v24
	s_waitcnt lgkmcnt(0)
	v_add_f32_e32 v24, v24, v25
	ds_bpermute_b32 v25, v139, v24
	s_waitcnt lgkmcnt(0)
	v_add_f32_e32 v24, v24, v25
	v_fmamk_f32 v24, v24, 0x3c000000, v140
	v_cmp_gt_f32_e32 vcc, s21, v24
	v_mul_f32_e32 v25, 0x4f800000, v24
	s_nop 0
	v_cndmask_b32_e32 v24, v24, v25, vcc
	v_sqrt_f32_e32 v25, v24
	s_nop 0
	v_add_u32_e32 v26, -1, v25
	v_fma_f32 v27, -v26, v25, v24
	v_cmp_ge_f32_e64 s[0:1], 0, v27
	v_add_u32_e32 v27, 1, v25
	s_nop 0
	v_cndmask_b32_e64 v26, v25, v26, s[0:1]
	v_fma_f32 v25, -v27, v25, v24
	v_cmp_lt_f32_e64 s[0:1], 0, v25
	s_nop 1
	v_cndmask_b32_e64 v25, v26, v27, s[0:1]
	v_mul_f32_e32 v26, 0x37800000, v25
	v_cndmask_b32_e32 v25, v25, v26, vcc
	v_cmp_class_f32_e32 vcc, v24, v141
	s_nop 1
	v_cndmask_b32_e32 v24, v25, v24, vcc
	v_div_scale_f32 v25, s[0:1], v24, v24, s22
	v_rcp_f32_e32 v26, v25
	s_nop 0
	v_fma_f32 v27, -v25, v26, 1.0
	v_fmac_f32_e32 v26, v27, v26
	v_div_scale_f32 v27, vcc, s22, v24, s22
	v_mul_f32_e32 v30, v27, v26
	v_fma_f32 v31, -v25, v30, v27
	v_fmac_f32_e32 v30, v31, v26
	v_fma_f32 v25, -v25, v30, v27
	v_div_fmas_f32 v25, v25, v26, v30
	v_div_fixup_f32 v24, v25, v24, s22
	v_pk_mul_f32 v[22:23], v[22:23], v[24:25] op_sel_hi:[1,0]
	v_pk_mul_f32 v[26:27], v[28:29], v[24:25] op_sel_hi:[1,0]
	v_pk_mul_f32 v[22:23], v[4:5], v[22:23]
	v_pk_mul_f32 v[26:27], v[2:3], v[26:27]
	v_pk_mul_f32 v[20:21], v[20:21], v[24:25] op_sel_hi:[1,0]
	v_pk_mul_f32 v[28:29], v[32:33], v[24:25] op_sel_hi:[1,0]
	v_bfe_u32 v24, v23, 16, 1
	v_bfe_u32 v25, v22, 16, 1
	v_pk_mul_f32 v[20:21], v[124:125], v[20:21]
	v_add3_u32 v22, v22, v25, s23
	v_add3_u32 v23, v23, v24, s23
	v_cvt_pk_bf16_f32 v20, v26, v20
	v_cvt_pk_bf16_f32 v21, v27, v21
	v_pk_mul_f32 v[28:29], v[6:7], v[28:29]
	v_bfe_u32 v30, v28, 16, 1
	v_bfe_u32 v31, v29, 16, 1
	v_add3_u32 v29, v29, v31, s23
	v_add3_u32 v28, v28, v30, s23
	v_lshl_add_u64 v[24:25], v[100:101], 0, v[98:99]
	v_lshrrev_b32_e32 v26, 16, v28
	v_lshrrev_b32_e32 v27, 16, v29
	v_add_co_u32_e32 v24, vcc, s24, v24
	v_and_or_b32 v23, v23, s20, v27
	v_and_or_b32 v22, v22, s20, v26
	v_addc_co_u32_e32 v25, vcc, -1, v25, vcc
	global_store_dwordx4 v[24:25], v[20:23], off offset:-256 sc1
	v_lshl_add_u64 v[98:99], v[98:99], 0, s[8:9]
	s_waitcnt vmcnt(10)
	v_max3_f32 v20, v142, v143, v144
	v_sub_f32_e32 v21, v142, v20
	v_exp_f32_e32 v23, v21
	v_sub_f32_e32 v21, v143, v20
	v_exp_f32_e32 v22, v21
	v_sub_f32_e32 v20, v144, v20
	v_exp_f32_e32 v20, v20
	v_add_f32_e32 v21, v23, v22
	v_add_f32_e32 v21, v20, v21
	v_div_scale_f32 v24, s[0:1], v21, v21, 1.0
	v_rcp_f32_e32 v25, v24
	s_nop 0
	v_fma_f32 v26, -v24, v25, 1.0
	v_fmac_f32_e32 v25, v26, v25
	v_div_scale_f32 v26, vcc, 1.0, v21, 1.0
	v_mul_f32_e32 v27, v26, v25
	v_fma_f32 v28, -v24, v27, v26
	v_fmac_f32_e32 v27, v28, v25
	v_fma_f32 v24, -v24, v27, v26
	v_div_fmas_f32 v24, v24, v25, v27
	v_div_fixup_f32 v24, v24, v21, 1.0
	v_pk_mul_f32 v[22:23], v[22:23], v[24:25] op_sel_hi:[1,0]
	s_waitcnt vmcnt(8)
	v_lshlrev_b32_e32 v27, 16, v17
	v_lshlrev_b32_e32 v26, 16, v12
	v_mul_f32_e32 v20, v20, v24
	v_lshlrev_b32_e32 v25, 16, v13
	v_lshlrev_b32_e32 v24, 16, v16
	v_pk_mul_f32 v[26:27], v[22:23], v[26:27] op_sel:[1,0] op_sel_hi:[0,1]
	v_pk_fma_f32 v[24:25], v[22:23], v[24:25], v[26:27]
	s_waitcnt vmcnt(7)
	v_lshlrev_b32_e32 v27, 16, v9
	v_lshlrev_b32_e32 v26, 16, v8
	v_pk_fma_f32 v[24:25], v[20:21], v[26:27], v[24:25] op_sel_hi:[0,1,1]
	v_and_b32_e32 v27, 0xffff0000, v13
	v_and_b32_e32 v13, 0xffff0000, v17
	v_and_b32_e32 v12, 0xffff0000, v12
	v_and_b32_e32 v26, 0xffff0000, v16
	v_pk_mul_f32 v[12:13], v[22:23], v[12:13] op_sel:[1,0] op_sel_hi:[0,1]
	v_pk_fma_f32 v[12:13], v[22:23], v[26:27], v[12:13]
	v_and_b32_e32 v9, 0xffff0000, v9
	v_and_b32_e32 v8, 0xffff0000, v8
	v_lshlrev_b32_e32 v17, 16, v19
	v_lshlrev_b32_e32 v16, 16, v14
	v_pk_fma_f32 v[8:9], v[20:21], v[8:9], v[12:13] op_sel_hi:[0,1,1]
	v_lshlrev_b32_e32 v13, 16, v15
	v_lshlrev_b32_e32 v12, 16, v18
	v_pk_mul_f32 v[16:17], v[22:23], v[16:17] op_sel:[1,0] op_sel_hi:[0,1]
	v_pk_fma_f32 v[12:13], v[22:23], v[12:13], v[16:17]
	v_lshlrev_b32_e32 v17, 16, v11
	v_lshlrev_b32_e32 v16, 16, v10
	v_pk_fma_f32 v[12:13], v[20:21], v[16:17], v[12:13] op_sel_hi:[0,1,1]
	v_and_b32_e32 v17, 0xffff0000, v15
	v_and_b32_e32 v15, 0xffff0000, v19
	v_and_b32_e32 v14, 0xffff0000, v14
	v_and_b32_e32 v16, 0xffff0000, v18
	v_pk_mul_f32 v[14:15], v[22:23], v[14:15] op_sel:[1,0] op_sel_hi:[0,1]
	v_pk_fma_f32 v[14:15], v[22:23], v[16:17], v[14:15]
	v_and_b32_e32 v11, 0xffff0000, v11
	v_and_b32_e32 v10, 0xffff0000, v10
	v_cvt_pk_bf16_f32 v9, v25, v9
	v_cvt_pk_bf16_f32 v8, v24, v8
	v_pk_fma_f32 v[10:11], v[20:21], v[10:11], v[14:15] op_sel_hi:[0,1,1]
	v_cvt_pk_bf16_f32 v10, v12, v10
	v_cvt_pk_bf16_f32 v11, v13, v11
	v_lshl_add_u64 v[12:13], v[88:89], 0, v[96:97]
	v_add_co_u32_e32 v12, vcc, s25, v12
	v_addc_co_u32_e32 v13, vcc, -1, v13, vcc
	v_lshl_add_u64 v[96:97], v[96:97], 0, s[8:9]
	global_store_dwordx4 v[12:13], v[8:11], off offset:-3072 sc1
	s_cbranch_scc1 .LBB0_495
